# v34: v25 + prep phase (adaLN GEMV + first weight conversion) write-through with flat barrier
# speedup vs baseline: 1.0107x; 1.0107x over previous
.LBB0_29:
	s_lshl_b64 s[98:99], s[12:13], 2
	s_add_u32 s98, s98, s4
	s_addc_u32 s99, s99, s5
	v_add_u32_e32 v200, v20, v22
	global_load_dword v80, v200, s[98:99]
	s_add_u32 s98, s98, 0x6000
	s_addc_u32 s99, s99, 0
	global_load_dword v81, v200, s[98:99]
	s_add_u32 s98, s98, 0x6000
	s_addc_u32 s99, s99, 0
	global_load_dword v82, v200, s[98:99]
	s_add_u32 s98, s98, 0x6000
	s_addc_u32 s99, s99, 0
	global_load_dword v83, v200, s[98:99]
	s_add_u32 s98, s98, 0x6000
	s_addc_u32 s99, s99, 0
	global_load_dword v84, v200, s[98:99]
	s_add_u32 s98, s98, 0x6000
	s_addc_u32 s99, s99, 0
	global_load_dword v85, v200, s[98:99]
	s_add_u32 s98, s98, 0x6000
	s_addc_u32 s99, s99, 0
	global_load_dword v86, v200, s[98:99]
	s_add_u32 s98, s98, 0x6000
	s_addc_u32 s99, s99, 0
	global_load_dword v87, v200, s[98:99]
	s_add_u32 s98, s98, 0x6000
	s_addc_u32 s99, s99, 0
	global_load_dword v88, v200, s[98:99]
	s_add_u32 s98, s98, 0x6000
	s_addc_u32 s99, s99, 0
	global_load_dword v89, v200, s[98:99]
	s_add_u32 s98, s98, 0x6000
	s_addc_u32 s99, s99, 0
	global_load_dword v90, v200, s[98:99]
	s_add_u32 s98, s98, 0x6000
	s_addc_u32 s99, s99, 0
	global_load_dword v91, v200, s[98:99]
	s_add_u32 s98, s98, 0x6000
	s_addc_u32 s99, s99, 0
	global_load_dword v92, v200, s[98:99]
	s_add_u32 s98, s98, 0x6000
	s_addc_u32 s99, s99, 0
	global_load_dword v93, v200, s[98:99]
	s_add_u32 s98, s98, 0x6000
	s_addc_u32 s99, s99, 0
	global_load_dword v94, v200, s[98:99]
	s_add_u32 s98, s98, 0x6000
	s_addc_u32 s99, s99, 0
	global_load_dword v95, v200, s[98:99]
	s_add_u32 s98, s98, 0x6000
	s_addc_u32 s99, s99, 0
	global_load_dword v96, v200, s[98:99]
	s_add_u32 s98, s98, 0x6000
	s_addc_u32 s99, s99, 0
	global_load_dword v97, v200, s[98:99]
	s_add_u32 s98, s98, 0x6000
	s_addc_u32 s99, s99, 0
	global_load_dword v98, v200, s[98:99]
	s_add_u32 s98, s98, 0x6000
	s_addc_u32 s99, s99, 0
	global_load_dword v99, v200, s[98:99]
	s_add_u32 s98, s98, 0x6000
	s_addc_u32 s99, s99, 0
	global_load_dword v100, v200, s[98:99]
	s_add_u32 s98, s98, 0x6000
	s_addc_u32 s99, s99, 0
	global_load_dword v101, v200, s[98:99]
	s_add_u32 s98, s98, 0x6000
	s_addc_u32 s99, s99, 0
	global_load_dword v102, v200, s[98:99]
	s_add_u32 s98, s98, 0x6000
	s_addc_u32 s99, s99, 0
	global_load_dword v103, v200, s[98:99]
	s_add_u32 s98, s98, 0x6000
	s_addc_u32 s99, s99, 0
	global_load_dword v104, v200, s[98:99]
	s_add_u32 s98, s98, 0x6000
	s_addc_u32 s99, s99, 0
	global_load_dword v105, v200, s[98:99]
	s_add_u32 s98, s98, 0x6000
	s_addc_u32 s99, s99, 0
	global_load_dword v106, v200, s[98:99]
	s_add_u32 s98, s98, 0x6000
	s_addc_u32 s99, s99, 0
	global_load_dword v107, v200, s[98:99]
	s_add_u32 s98, s98, 0x6000
	s_addc_u32 s99, s99, 0
	global_load_dword v108, v200, s[98:99]
	s_add_u32 s98, s98, 0x6000
	s_addc_u32 s99, s99, 0
	global_load_dword v109, v200, s[98:99]
	s_add_u32 s98, s98, 0x6000
	s_addc_u32 s99, s99, 0
	global_load_dword v110, v200, s[98:99]
	s_add_u32 s98, s98, 0x6000
	s_addc_u32 s99, s99, 0
	global_load_dword v111, v200, s[98:99]
	s_add_u32 s98, s98, 0x6000
	s_addc_u32 s99, s99, 0
	global_load_dword v112, v200, s[98:99]
	s_add_u32 s98, s98, 0x6000
	s_addc_u32 s99, s99, 0
	global_load_dword v113, v200, s[98:99]
	s_add_u32 s98, s98, 0x6000
	s_addc_u32 s99, s99, 0
	global_load_dword v114, v200, s[98:99]
	s_add_u32 s98, s98, 0x6000
	s_addc_u32 s99, s99, 0
	global_load_dword v115, v200, s[98:99]
	s_add_u32 s98, s98, 0x6000
	s_addc_u32 s99, s99, 0
	global_load_dword v116, v200, s[98:99]
	s_add_u32 s98, s98, 0x6000
	s_addc_u32 s99, s99, 0
	global_load_dword v117, v200, s[98:99]
	s_add_u32 s98, s98, 0x6000
	s_addc_u32 s99, s99, 0
	global_load_dword v118, v200, s[98:99]
	s_add_u32 s98, s98, 0x6000
	s_addc_u32 s99, s99, 0
	global_load_dword v119, v200, s[98:99]
	s_add_u32 s98, s98, 0x6000
	s_addc_u32 s99, s99, 0
	global_load_dword v120, v200, s[98:99]
	s_add_u32 s98, s98, 0x6000
	s_addc_u32 s99, s99, 0
	global_load_dword v121, v200, s[98:99]
	s_add_u32 s98, s98, 0x6000
	s_addc_u32 s99, s99, 0
	global_load_dword v122, v200, s[98:99]
	s_add_u32 s98, s98, 0x6000
	s_addc_u32 s99, s99, 0
	global_load_dword v123, v200, s[98:99]
	s_add_u32 s98, s98, 0x6000
	s_addc_u32 s99, s99, 0
	global_load_dword v124, v200, s[98:99]
	s_add_u32 s98, s98, 0x6000
	s_addc_u32 s99, s99, 0
	global_load_dword v125, v200, s[98:99]
	s_add_u32 s98, s98, 0x6000
	s_addc_u32 s99, s99, 0
	global_load_dword v126, v200, s[98:99]
	s_add_u32 s98, s98, 0x6000
	s_addc_u32 s99, s99, 0
	global_load_dword v127, v200, s[98:99]
	s_add_u32 s98, s98, 0x6000
	s_addc_u32 s99, s99, 0
	global_load_dword v128, v200, s[98:99]
	s_add_u32 s98, s98, 0x6000
	s_addc_u32 s99, s99, 0
	global_load_dword v129, v200, s[98:99]
	s_add_u32 s98, s98, 0x6000
	s_addc_u32 s99, s99, 0
	global_load_dword v130, v200, s[98:99]
	s_add_u32 s98, s98, 0x6000
	s_addc_u32 s99, s99, 0
	global_load_dword v131, v200, s[98:99]
	s_add_u32 s98, s98, 0x6000
	s_addc_u32 s99, s99, 0
	global_load_dword v132, v200, s[98:99]
	s_add_u32 s98, s98, 0x6000
	s_addc_u32 s99, s99, 0
	global_load_dword v133, v200, s[98:99]
	s_add_u32 s98, s98, 0x6000
	s_addc_u32 s99, s99, 0
	global_load_dword v134, v200, s[98:99]
	s_add_u32 s98, s98, 0x6000
	s_addc_u32 s99, s99, 0
	global_load_dword v135, v200, s[98:99]
	s_add_u32 s98, s98, 0x6000
	s_addc_u32 s99, s99, 0
	global_load_dword v136, v200, s[98:99]
	s_add_u32 s98, s98, 0x6000
	s_addc_u32 s99, s99, 0
	global_load_dword v137, v200, s[98:99]
	s_add_u32 s98, s98, 0x6000
	s_addc_u32 s99, s99, 0
	global_load_dword v138, v200, s[98:99]
	s_add_u32 s98, s98, 0x6000
	s_addc_u32 s99, s99, 0
	global_load_dword v139, v200, s[98:99]
	s_add_u32 s98, s98, 0x6000
	s_addc_u32 s99, s99, 0
	global_load_dword v140, v200, s[98:99]
	s_add_u32 s98, s98, 0x6000
	s_addc_u32 s99, s99, 0
	global_load_dword v141, v200, s[98:99]
	s_add_u32 s98, s98, 0x6000
	s_addc_u32 s99, s99, 0
	global_load_dword v142, v200, s[98:99]
	s_add_u32 s98, s98, 0x6000
	s_addc_u32 s99, s99, 0
	global_load_dword v143, v200, s[98:99]
	s_add_u32 s98, s98, 0x6000
	s_addc_u32 s99, s99, 0
	ds_read_b128 v[144:147], v35
	ds_read_b128 v[148:151], v35 offset:4096
	ds_read_b128 v[152:155], v35 offset:8192
	s_waitcnt vmcnt(32)
	ds_read_b128 v[156:159], v35 offset:16
	ds_read_b128 v[160:163], v35 offset:4112
	ds_read_b128 v[164:167], v35 offset:8208
	s_waitcnt lgkmcnt(3)
	v_fmac_f32_e32 v30, v80, v144
	v_fmac_f32_e32 v34, v80, v148
	v_fmac_f32_e32 v31, v80, v152
	v_fmac_f32_e32 v30, v81, v145
	v_fmac_f32_e32 v34, v81, v149
	v_fmac_f32_e32 v31, v81, v153
	v_fmac_f32_e32 v30, v82, v146
	v_fmac_f32_e32 v34, v82, v150
	v_fmac_f32_e32 v31, v82, v154
	v_fmac_f32_e32 v30, v83, v147
	v_fmac_f32_e32 v34, v83, v151
	v_fmac_f32_e32 v31, v83, v155
	ds_read_b128 v[144:147], v35 offset:32
	ds_read_b128 v[148:151], v35 offset:4128
	ds_read_b128 v[152:155], v35 offset:8224
	s_waitcnt lgkmcnt(3)
	v_fmac_f32_e32 v30, v84, v156
	v_fmac_f32_e32 v34, v84, v160
	v_fmac_f32_e32 v31, v84, v164
	v_fmac_f32_e32 v30, v85, v157
	v_fmac_f32_e32 v34, v85, v161
	v_fmac_f32_e32 v31, v85, v165
	v_fmac_f32_e32 v30, v86, v158
	v_fmac_f32_e32 v34, v86, v162
	v_fmac_f32_e32 v31, v86, v166
	v_fmac_f32_e32 v30, v87, v159
	v_fmac_f32_e32 v34, v87, v163
	v_fmac_f32_e32 v31, v87, v167
	ds_read_b128 v[156:159], v35 offset:48
	ds_read_b128 v[160:163], v35 offset:4144
	ds_read_b128 v[164:167], v35 offset:8240
	s_waitcnt lgkmcnt(3)
	v_fmac_f32_e32 v30, v88, v144
	v_fmac_f32_e32 v34, v88, v148
	v_fmac_f32_e32 v31, v88, v152
	v_fmac_f32_e32 v30, v89, v145
	v_fmac_f32_e32 v34, v89, v149
	v_fmac_f32_e32 v31, v89, v153
	v_fmac_f32_e32 v30, v90, v146
	v_fmac_f32_e32 v34, v90, v150
	v_fmac_f32_e32 v31, v90, v154
	v_fmac_f32_e32 v30, v91, v147
	v_fmac_f32_e32 v34, v91, v151
	v_fmac_f32_e32 v31, v91, v155
	ds_read_b128 v[144:147], v35 offset:64
	ds_read_b128 v[148:151], v35 offset:4160
	ds_read_b128 v[152:155], v35 offset:8256
	s_waitcnt lgkmcnt(3)
	v_fmac_f32_e32 v30, v92, v156
	v_fmac_f32_e32 v34, v92, v160
	v_fmac_f32_e32 v31, v92, v164
	v_fmac_f32_e32 v30, v93, v157
	v_fmac_f32_e32 v34, v93, v161
	v_fmac_f32_e32 v31, v93, v165
	v_fmac_f32_e32 v30, v94, v158
	v_fmac_f32_e32 v34, v94, v162
	v_fmac_f32_e32 v31, v94, v166
	v_fmac_f32_e32 v30, v95, v159
	v_fmac_f32_e32 v34, v95, v163
	v_fmac_f32_e32 v31, v95, v167
	ds_read_b128 v[156:159], v35 offset:80
	ds_read_b128 v[160:163], v35 offset:4176
	ds_read_b128 v[164:167], v35 offset:8272
	s_waitcnt lgkmcnt(3)
	v_fmac_f32_e32 v30, v96, v144
	v_fmac_f32_e32 v34, v96, v148
	v_fmac_f32_e32 v31, v96, v152
	v_fmac_f32_e32 v30, v97, v145
	v_fmac_f32_e32 v34, v97, v149
	v_fmac_f32_e32 v31, v97, v153
	v_fmac_f32_e32 v30, v98, v146
	v_fmac_f32_e32 v34, v98, v150
	v_fmac_f32_e32 v31, v98, v154
	v_fmac_f32_e32 v30, v99, v147
	v_fmac_f32_e32 v34, v99, v151
	v_fmac_f32_e32 v31, v99, v155
	ds_read_b128 v[144:147], v35 offset:96
	ds_read_b128 v[148:151], v35 offset:4192
	ds_read_b128 v[152:155], v35 offset:8288
	s_waitcnt lgkmcnt(3)
	v_fmac_f32_e32 v30, v100, v156
	v_fmac_f32_e32 v34, v100, v160
	v_fmac_f32_e32 v31, v100, v164
	v_fmac_f32_e32 v30, v101, v157
	v_fmac_f32_e32 v34, v101, v161
	v_fmac_f32_e32 v31, v101, v165
	v_fmac_f32_e32 v30, v102, v158
	v_fmac_f32_e32 v34, v102, v162
	v_fmac_f32_e32 v31, v102, v166
	v_fmac_f32_e32 v30, v103, v159
	v_fmac_f32_e32 v34, v103, v163
	v_fmac_f32_e32 v31, v103, v167
	ds_read_b128 v[156:159], v35 offset:112
	ds_read_b128 v[160:163], v35 offset:4208
	ds_read_b128 v[164:167], v35 offset:8304
	s_waitcnt lgkmcnt(3)
	v_fmac_f32_e32 v30, v104, v144
	v_fmac_f32_e32 v34, v104, v148
	v_fmac_f32_e32 v31, v104, v152
	v_fmac_f32_e32 v30, v105, v145
	v_fmac_f32_e32 v34, v105, v149
	v_fmac_f32_e32 v31, v105, v153
	v_fmac_f32_e32 v30, v106, v146
	v_fmac_f32_e32 v34, v106, v150
	v_fmac_f32_e32 v31, v106, v154
	v_fmac_f32_e32 v30, v107, v147
	v_fmac_f32_e32 v34, v107, v151
	v_fmac_f32_e32 v31, v107, v155
	ds_read_b128 v[144:147], v35 offset:128
	ds_read_b128 v[148:151], v35 offset:4224
	ds_read_b128 v[152:155], v35 offset:8320
	s_waitcnt lgkmcnt(3)
	v_fmac_f32_e32 v30, v108, v156
	v_fmac_f32_e32 v34, v108, v160
	v_fmac_f32_e32 v31, v108, v164
	v_fmac_f32_e32 v30, v109, v157
	v_fmac_f32_e32 v34, v109, v161
	v_fmac_f32_e32 v31, v109, v165
	v_fmac_f32_e32 v30, v110, v158
	v_fmac_f32_e32 v34, v110, v162
	v_fmac_f32_e32 v31, v110, v166
	v_fmac_f32_e32 v30, v111, v159
	v_fmac_f32_e32 v34, v111, v163
	v_fmac_f32_e32 v31, v111, v167
	global_load_dword v80, v200, s[98:99]
	s_add_u32 s98, s98, 0x6000
	s_addc_u32 s99, s99, 0
	global_load_dword v81, v200, s[98:99]
	s_add_u32 s98, s98, 0x6000
	s_addc_u32 s99, s99, 0
	global_load_dword v82, v200, s[98:99]
	s_add_u32 s98, s98, 0x6000
	s_addc_u32 s99, s99, 0
	global_load_dword v83, v200, s[98:99]
	s_add_u32 s98, s98, 0x6000
	s_addc_u32 s99, s99, 0
	global_load_dword v84, v200, s[98:99]
	s_add_u32 s98, s98, 0x6000
	s_addc_u32 s99, s99, 0
	global_load_dword v85, v200, s[98:99]
	s_add_u32 s98, s98, 0x6000
	s_addc_u32 s99, s99, 0
	global_load_dword v86, v200, s[98:99]
	s_add_u32 s98, s98, 0x6000
	s_addc_u32 s99, s99, 0
	global_load_dword v87, v200, s[98:99]
	s_add_u32 s98, s98, 0x6000
	s_addc_u32 s99, s99, 0
	global_load_dword v88, v200, s[98:99]
	s_add_u32 s98, s98, 0x6000
	s_addc_u32 s99, s99, 0
	global_load_dword v89, v200, s[98:99]
	s_add_u32 s98, s98, 0x6000
	s_addc_u32 s99, s99, 0
	global_load_dword v90, v200, s[98:99]
	s_add_u32 s98, s98, 0x6000
	s_addc_u32 s99, s99, 0
	global_load_dword v91, v200, s[98:99]
	s_add_u32 s98, s98, 0x6000
	s_addc_u32 s99, s99, 0
	global_load_dword v92, v200, s[98:99]
	s_add_u32 s98, s98, 0x6000
	s_addc_u32 s99, s99, 0
	global_load_dword v93, v200, s[98:99]
	s_add_u32 s98, s98, 0x6000
	s_addc_u32 s99, s99, 0
	global_load_dword v94, v200, s[98:99]
	s_add_u32 s98, s98, 0x6000
	s_addc_u32 s99, s99, 0
	global_load_dword v95, v200, s[98:99]
	s_add_u32 s98, s98, 0x6000
	s_addc_u32 s99, s99, 0
	global_load_dword v96, v200, s[98:99]
	s_add_u32 s98, s98, 0x6000
	s_addc_u32 s99, s99, 0
	global_load_dword v97, v200, s[98:99]
	s_add_u32 s98, s98, 0x6000
	s_addc_u32 s99, s99, 0
	global_load_dword v98, v200, s[98:99]
	s_add_u32 s98, s98, 0x6000
	s_addc_u32 s99, s99, 0
	global_load_dword v99, v200, s[98:99]
	s_add_u32 s98, s98, 0x6000
	s_addc_u32 s99, s99, 0
	global_load_dword v100, v200, s[98:99]
	s_add_u32 s98, s98, 0x6000
	s_addc_u32 s99, s99, 0
	global_load_dword v101, v200, s[98:99]
	s_add_u32 s98, s98, 0x6000
	s_addc_u32 s99, s99, 0
	global_load_dword v102, v200, s[98:99]
	s_add_u32 s98, s98, 0x6000
	s_addc_u32 s99, s99, 0
	global_load_dword v103, v200, s[98:99]
	s_add_u32 s98, s98, 0x6000
	s_addc_u32 s99, s99, 0
	global_load_dword v104, v200, s[98:99]
	s_add_u32 s98, s98, 0x6000
	s_addc_u32 s99, s99, 0
	global_load_dword v105, v200, s[98:99]
	s_add_u32 s98, s98, 0x6000
	s_addc_u32 s99, s99, 0
	global_load_dword v106, v200, s[98:99]
	s_add_u32 s98, s98, 0x6000
	s_addc_u32 s99, s99, 0
	global_load_dword v107, v200, s[98:99]
	s_add_u32 s98, s98, 0x6000
	s_addc_u32 s99, s99, 0
	global_load_dword v108, v200, s[98:99]
	s_add_u32 s98, s98, 0x6000
	s_addc_u32 s99, s99, 0
	global_load_dword v109, v200, s[98:99]
	s_add_u32 s98, s98, 0x6000
	s_addc_u32 s99, s99, 0
	global_load_dword v110, v200, s[98:99]
	s_add_u32 s98, s98, 0x6000
	s_addc_u32 s99, s99, 0
	global_load_dword v111, v200, s[98:99]
	s_add_u32 s98, s98, 0x6000
	s_addc_u32 s99, s99, 0
	s_waitcnt vmcnt(32)
	ds_read_b128 v[156:159], v35 offset:144
	ds_read_b128 v[160:163], v35 offset:4240
	ds_read_b128 v[164:167], v35 offset:8336
	s_waitcnt lgkmcnt(3)
	v_fmac_f32_e32 v30, v112, v144
	v_fmac_f32_e32 v34, v112, v148
	v_fmac_f32_e32 v31, v112, v152
	v_fmac_f32_e32 v30, v113, v145
	v_fmac_f32_e32 v34, v113, v149
	v_fmac_f32_e32 v31, v113, v153
	v_fmac_f32_e32 v30, v114, v146
	v_fmac_f32_e32 v34, v114, v150
	v_fmac_f32_e32 v31, v114, v154
	v_fmac_f32_e32 v30, v115, v147
	v_fmac_f32_e32 v34, v115, v151
	v_fmac_f32_e32 v31, v115, v155
	ds_read_b128 v[144:147], v35 offset:160
	ds_read_b128 v[148:151], v35 offset:4256
	ds_read_b128 v[152:155], v35 offset:8352
	s_waitcnt lgkmcnt(3)
	v_fmac_f32_e32 v30, v116, v156
	v_fmac_f32_e32 v34, v116, v160
	v_fmac_f32_e32 v31, v116, v164
	v_fmac_f32_e32 v30, v117, v157
	v_fmac_f32_e32 v34, v117, v161
	v_fmac_f32_e32 v31, v117, v165
	v_fmac_f32_e32 v30, v118, v158
	v_fmac_f32_e32 v34, v118, v162
	v_fmac_f32_e32 v31, v118, v166
	v_fmac_f32_e32 v30, v119, v159
	v_fmac_f32_e32 v34, v119, v163
	v_fmac_f32_e32 v31, v119, v167
	ds_read_b128 v[156:159], v35 offset:176
	ds_read_b128 v[160:163], v35 offset:4272
	ds_read_b128 v[164:167], v35 offset:8368
	s_waitcnt lgkmcnt(3)
	v_fmac_f32_e32 v30, v120, v144
	v_fmac_f32_e32 v34, v120, v148
	v_fmac_f32_e32 v31, v120, v152
	v_fmac_f32_e32 v30, v121, v145
	v_fmac_f32_e32 v34, v121, v149
	v_fmac_f32_e32 v31, v121, v153
	v_fmac_f32_e32 v30, v122, v146
	v_fmac_f32_e32 v34, v122, v150
	v_fmac_f32_e32 v31, v122, v154
	v_fmac_f32_e32 v30, v123, v147
	v_fmac_f32_e32 v34, v123, v151
	v_fmac_f32_e32 v31, v123, v155
	ds_read_b128 v[144:147], v35 offset:192
	ds_read_b128 v[148:151], v35 offset:4288
	ds_read_b128 v[152:155], v35 offset:8384
	s_waitcnt lgkmcnt(3)
	v_fmac_f32_e32 v30, v124, v156
	v_fmac_f32_e32 v34, v124, v160
	v_fmac_f32_e32 v31, v124, v164
	v_fmac_f32_e32 v30, v125, v157
	v_fmac_f32_e32 v34, v125, v161
	v_fmac_f32_e32 v31, v125, v165
	v_fmac_f32_e32 v30, v126, v158
	v_fmac_f32_e32 v34, v126, v162
	v_fmac_f32_e32 v31, v126, v166
	v_fmac_f32_e32 v30, v127, v159
	v_fmac_f32_e32 v34, v127, v163
	v_fmac_f32_e32 v31, v127, v167
	ds_read_b128 v[156:159], v35 offset:208
	ds_read_b128 v[160:163], v35 offset:4304
	ds_read_b128 v[164:167], v35 offset:8400
	s_waitcnt lgkmcnt(3)
	v_fmac_f32_e32 v30, v128, v144
	v_fmac_f32_e32 v34, v128, v148
	v_fmac_f32_e32 v31, v128, v152
	v_fmac_f32_e32 v30, v129, v145
	v_fmac_f32_e32 v34, v129, v149
	v_fmac_f32_e32 v31, v129, v153
	v_fmac_f32_e32 v30, v130, v146
	v_fmac_f32_e32 v34, v130, v150
	v_fmac_f32_e32 v31, v130, v154
	v_fmac_f32_e32 v30, v131, v147
	v_fmac_f32_e32 v34, v131, v151
	v_fmac_f32_e32 v31, v131, v155
	ds_read_b128 v[144:147], v35 offset:224
	ds_read_b128 v[148:151], v35 offset:4320
	ds_read_b128 v[152:155], v35 offset:8416
	s_waitcnt lgkmcnt(3)
	v_fmac_f32_e32 v30, v132, v156
	v_fmac_f32_e32 v34, v132, v160
	v_fmac_f32_e32 v31, v132, v164
	v_fmac_f32_e32 v30, v133, v157
	v_fmac_f32_e32 v34, v133, v161
	v_fmac_f32_e32 v31, v133, v165
	v_fmac_f32_e32 v30, v134, v158
	v_fmac_f32_e32 v34, v134, v162
	v_fmac_f32_e32 v31, v134, v166
	v_fmac_f32_e32 v30, v135, v159
	v_fmac_f32_e32 v34, v135, v163
	v_fmac_f32_e32 v31, v135, v167
	ds_read_b128 v[156:159], v35 offset:240
	ds_read_b128 v[160:163], v35 offset:4336
	ds_read_b128 v[164:167], v35 offset:8432
	s_waitcnt lgkmcnt(3)
	v_fmac_f32_e32 v30, v136, v144
	v_fmac_f32_e32 v34, v136, v148
	v_fmac_f32_e32 v31, v136, v152
	v_fmac_f32_e32 v30, v137, v145
	v_fmac_f32_e32 v34, v137, v149
	v_fmac_f32_e32 v31, v137, v153
	v_fmac_f32_e32 v30, v138, v146
	v_fmac_f32_e32 v34, v138, v150
	v_fmac_f32_e32 v31, v138, v154
	v_fmac_f32_e32 v30, v139, v147
	v_fmac_f32_e32 v34, v139, v151
	v_fmac_f32_e32 v31, v139, v155
	ds_read_b128 v[144:147], v35 offset:256
	ds_read_b128 v[148:151], v35 offset:4352
	ds_read_b128 v[152:155], v35 offset:8448
	s_waitcnt lgkmcnt(3)
	v_fmac_f32_e32 v30, v140, v156
	v_fmac_f32_e32 v34, v140, v160
	v_fmac_f32_e32 v31, v140, v164
	v_fmac_f32_e32 v30, v141, v157
	v_fmac_f32_e32 v34, v141, v161
	v_fmac_f32_e32 v31, v141, v165
	v_fmac_f32_e32 v30, v142, v158
	v_fmac_f32_e32 v34, v142, v162
	v_fmac_f32_e32 v31, v142, v166
	v_fmac_f32_e32 v30, v143, v159
	v_fmac_f32_e32 v34, v143, v163
	v_fmac_f32_e32 v31, v143, v167
	global_load_dword v112, v200, s[98:99]
	s_add_u32 s98, s98, 0x6000
	s_addc_u32 s99, s99, 0
	global_load_dword v113, v200, s[98:99]
	s_add_u32 s98, s98, 0x6000
	s_addc_u32 s99, s99, 0
	global_load_dword v114, v200, s[98:99]
	s_add_u32 s98, s98, 0x6000
	s_addc_u32 s99, s99, 0
	global_load_dword v115, v200, s[98:99]
	s_add_u32 s98, s98, 0x6000
	s_addc_u32 s99, s99, 0
	global_load_dword v116, v200, s[98:99]
	s_add_u32 s98, s98, 0x6000
	s_addc_u32 s99, s99, 0
	global_load_dword v117, v200, s[98:99]
	s_add_u32 s98, s98, 0x6000
	s_addc_u32 s99, s99, 0
	global_load_dword v118, v200, s[98:99]
	s_add_u32 s98, s98, 0x6000
	s_addc_u32 s99, s99, 0
	global_load_dword v119, v200, s[98:99]
	s_add_u32 s98, s98, 0x6000
	s_addc_u32 s99, s99, 0
	global_load_dword v120, v200, s[98:99]
	s_add_u32 s98, s98, 0x6000
	s_addc_u32 s99, s99, 0
	global_load_dword v121, v200, s[98:99]
	s_add_u32 s98, s98, 0x6000
	s_addc_u32 s99, s99, 0
	global_load_dword v122, v200, s[98:99]
	s_add_u32 s98, s98, 0x6000
	s_addc_u32 s99, s99, 0
	global_load_dword v123, v200, s[98:99]
	s_add_u32 s98, s98, 0x6000
	s_addc_u32 s99, s99, 0
	global_load_dword v124, v200, s[98:99]
	s_add_u32 s98, s98, 0x6000
	s_addc_u32 s99, s99, 0
	global_load_dword v125, v200, s[98:99]
	s_add_u32 s98, s98, 0x6000
	s_addc_u32 s99, s99, 0
	global_load_dword v126, v200, s[98:99]
	s_add_u32 s98, s98, 0x6000
	s_addc_u32 s99, s99, 0
	global_load_dword v127, v200, s[98:99]
	s_add_u32 s98, s98, 0x6000
	s_addc_u32 s99, s99, 0
	global_load_dword v128, v200, s[98:99]
	s_add_u32 s98, s98, 0x6000
	s_addc_u32 s99, s99, 0
	global_load_dword v129, v200, s[98:99]
	s_add_u32 s98, s98, 0x6000
	s_addc_u32 s99, s99, 0
	global_load_dword v130, v200, s[98:99]
	s_add_u32 s98, s98, 0x6000
	s_addc_u32 s99, s99, 0
	global_load_dword v131, v200, s[98:99]
	s_add_u32 s98, s98, 0x6000
	s_addc_u32 s99, s99, 0
	global_load_dword v132, v200, s[98:99]
	s_add_u32 s98, s98, 0x6000
	s_addc_u32 s99, s99, 0
	global_load_dword v133, v200, s[98:99]
	s_add_u32 s98, s98, 0x6000
	s_addc_u32 s99, s99, 0
	global_load_dword v134, v200, s[98:99]
	s_add_u32 s98, s98, 0x6000
	s_addc_u32 s99, s99, 0
	global_load_dword v135, v200, s[98:99]
	s_add_u32 s98, s98, 0x6000
	s_addc_u32 s99, s99, 0
	global_load_dword v136, v200, s[98:99]
	s_add_u32 s98, s98, 0x6000
	s_addc_u32 s99, s99, 0
	global_load_dword v137, v200, s[98:99]
	s_add_u32 s98, s98, 0x6000
	s_addc_u32 s99, s99, 0
	global_load_dword v138, v200, s[98:99]
	s_add_u32 s98, s98, 0x6000
	s_addc_u32 s99, s99, 0
	global_load_dword v139, v200, s[98:99]
	s_add_u32 s98, s98, 0x6000
	s_addc_u32 s99, s99, 0
	global_load_dword v140, v200, s[98:99]
	s_add_u32 s98, s98, 0x6000
	s_addc_u32 s99, s99, 0
	global_load_dword v141, v200, s[98:99]
	s_add_u32 s98, s98, 0x6000
	s_addc_u32 s99, s99, 0
	global_load_dword v142, v200, s[98:99]
	s_add_u32 s98, s98, 0x6000
	s_addc_u32 s99, s99, 0
	global_load_dword v143, v200, s[98:99]
	s_add_u32 s98, s98, 0x6000
	s_addc_u32 s99, s99, 0
	s_waitcnt vmcnt(32)
	ds_read_b128 v[156:159], v35 offset:272
	ds_read_b128 v[160:163], v35 offset:4368
	ds_read_b128 v[164:167], v35 offset:8464
	s_waitcnt lgkmcnt(3)
	v_fmac_f32_e32 v30, v80, v144
	v_fmac_f32_e32 v34, v80, v148
	v_fmac_f32_e32 v31, v80, v152
	v_fmac_f32_e32 v30, v81, v145
	v_fmac_f32_e32 v34, v81, v149
	v_fmac_f32_e32 v31, v81, v153
	v_fmac_f32_e32 v30, v82, v146
	v_fmac_f32_e32 v34, v82, v150
	v_fmac_f32_e32 v31, v82, v154
	v_fmac_f32_e32 v30, v83, v147
	v_fmac_f32_e32 v34, v83, v151
	v_fmac_f32_e32 v31, v83, v155
	ds_read_b128 v[144:147], v35 offset:288
	ds_read_b128 v[148:151], v35 offset:4384
	ds_read_b128 v[152:155], v35 offset:8480
	s_waitcnt lgkmcnt(3)
	v_fmac_f32_e32 v30, v84, v156
	v_fmac_f32_e32 v34, v84, v160
	v_fmac_f32_e32 v31, v84, v164
	v_fmac_f32_e32 v30, v85, v157
	v_fmac_f32_e32 v34, v85, v161
	v_fmac_f32_e32 v31, v85, v165
	v_fmac_f32_e32 v30, v86, v158
	v_fmac_f32_e32 v34, v86, v162
	v_fmac_f32_e32 v31, v86, v166
	v_fmac_f32_e32 v30, v87, v159
	v_fmac_f32_e32 v34, v87, v163
	v_fmac_f32_e32 v31, v87, v167
	ds_read_b128 v[156:159], v35 offset:304
	ds_read_b128 v[160:163], v35 offset:4400
	ds_read_b128 v[164:167], v35 offset:8496
	s_waitcnt lgkmcnt(3)
	v_fmac_f32_e32 v30, v88, v144
	v_fmac_f32_e32 v34, v88, v148
	v_fmac_f32_e32 v31, v88, v152
	v_fmac_f32_e32 v30, v89, v145
	v_fmac_f32_e32 v34, v89, v149
	v_fmac_f32_e32 v31, v89, v153
	v_fmac_f32_e32 v30, v90, v146
	v_fmac_f32_e32 v34, v90, v150
	v_fmac_f32_e32 v31, v90, v154
	v_fmac_f32_e32 v30, v91, v147
	v_fmac_f32_e32 v34, v91, v151
	v_fmac_f32_e32 v31, v91, v155
	ds_read_b128 v[144:147], v35 offset:320
	ds_read_b128 v[148:151], v35 offset:4416
	ds_read_b128 v[152:155], v35 offset:8512
	s_waitcnt lgkmcnt(3)
	v_fmac_f32_e32 v30, v92, v156
	v_fmac_f32_e32 v34, v92, v160
	v_fmac_f32_e32 v31, v92, v164
	v_fmac_f32_e32 v30, v93, v157
	v_fmac_f32_e32 v34, v93, v161
	v_fmac_f32_e32 v31, v93, v165
	v_fmac_f32_e32 v30, v94, v158
	v_fmac_f32_e32 v34, v94, v162
	v_fmac_f32_e32 v31, v94, v166
	v_fmac_f32_e32 v30, v95, v159
	v_fmac_f32_e32 v34, v95, v163
	v_fmac_f32_e32 v31, v95, v167
	ds_read_b128 v[156:159], v35 offset:336
	ds_read_b128 v[160:163], v35 offset:4432
	ds_read_b128 v[164:167], v35 offset:8528
	s_waitcnt lgkmcnt(3)
	v_fmac_f32_e32 v30, v96, v144
	v_fmac_f32_e32 v34, v96, v148
	v_fmac_f32_e32 v31, v96, v152
	v_fmac_f32_e32 v30, v97, v145
	v_fmac_f32_e32 v34, v97, v149
	v_fmac_f32_e32 v31, v97, v153
	v_fmac_f32_e32 v30, v98, v146
	v_fmac_f32_e32 v34, v98, v150
	v_fmac_f32_e32 v31, v98, v154
	v_fmac_f32_e32 v30, v99, v147
	v_fmac_f32_e32 v34, v99, v151
	v_fmac_f32_e32 v31, v99, v155
	ds_read_b128 v[144:147], v35 offset:352
	ds_read_b128 v[148:151], v35 offset:4448
	ds_read_b128 v[152:155], v35 offset:8544
	s_waitcnt lgkmcnt(3)
	v_fmac_f32_e32 v30, v100, v156
	v_fmac_f32_e32 v34, v100, v160
	v_fmac_f32_e32 v31, v100, v164
	v_fmac_f32_e32 v30, v101, v157
	v_fmac_f32_e32 v34, v101, v161
	v_fmac_f32_e32 v31, v101, v165
	v_fmac_f32_e32 v30, v102, v158
	v_fmac_f32_e32 v34, v102, v162
	v_fmac_f32_e32 v31, v102, v166
	v_fmac_f32_e32 v30, v103, v159
	v_fmac_f32_e32 v34, v103, v163
	v_fmac_f32_e32 v31, v103, v167
	ds_read_b128 v[156:159], v35 offset:368
	ds_read_b128 v[160:163], v35 offset:4464
	ds_read_b128 v[164:167], v35 offset:8560
	s_waitcnt lgkmcnt(3)
	v_fmac_f32_e32 v30, v104, v144
	v_fmac_f32_e32 v34, v104, v148
	v_fmac_f32_e32 v31, v104, v152
	v_fmac_f32_e32 v30, v105, v145
	v_fmac_f32_e32 v34, v105, v149
	v_fmac_f32_e32 v31, v105, v153
	v_fmac_f32_e32 v30, v106, v146
	v_fmac_f32_e32 v34, v106, v150
	v_fmac_f32_e32 v31, v106, v154
	v_fmac_f32_e32 v30, v107, v147
	v_fmac_f32_e32 v34, v107, v151
	v_fmac_f32_e32 v31, v107, v155
	ds_read_b128 v[144:147], v35 offset:384
	ds_read_b128 v[148:151], v35 offset:4480
	ds_read_b128 v[152:155], v35 offset:8576
	s_waitcnt lgkmcnt(3)
	v_fmac_f32_e32 v30, v108, v156
	v_fmac_f32_e32 v34, v108, v160
	v_fmac_f32_e32 v31, v108, v164
	v_fmac_f32_e32 v30, v109, v157
	v_fmac_f32_e32 v34, v109, v161
	v_fmac_f32_e32 v31, v109, v165
	v_fmac_f32_e32 v30, v110, v158
	v_fmac_f32_e32 v34, v110, v162
	v_fmac_f32_e32 v31, v110, v166
	v_fmac_f32_e32 v30, v111, v159
	v_fmac_f32_e32 v34, v111, v163
	v_fmac_f32_e32 v31, v111, v167
	s_waitcnt vmcnt(0)
	ds_read_b128 v[156:159], v35 offset:400
	ds_read_b128 v[160:163], v35 offset:4496
	ds_read_b128 v[164:167], v35 offset:8592
	s_waitcnt lgkmcnt(3)
	v_fmac_f32_e32 v30, v112, v144
	v_fmac_f32_e32 v34, v112, v148
	v_fmac_f32_e32 v31, v112, v152
	v_fmac_f32_e32 v30, v113, v145
	v_fmac_f32_e32 v34, v113, v149
	v_fmac_f32_e32 v31, v113, v153
	v_fmac_f32_e32 v30, v114, v146
	v_fmac_f32_e32 v34, v114, v150
	v_fmac_f32_e32 v31, v114, v154
	v_fmac_f32_e32 v30, v115, v147
	v_fmac_f32_e32 v34, v115, v151
	v_fmac_f32_e32 v31, v115, v155
	ds_read_b128 v[144:147], v35 offset:416
	ds_read_b128 v[148:151], v35 offset:4512
	ds_read_b128 v[152:155], v35 offset:8608
	s_waitcnt lgkmcnt(3)
	v_fmac_f32_e32 v30, v116, v156
	v_fmac_f32_e32 v34, v116, v160
	v_fmac_f32_e32 v31, v116, v164
	v_fmac_f32_e32 v30, v117, v157
	v_fmac_f32_e32 v34, v117, v161
	v_fmac_f32_e32 v31, v117, v165
	v_fmac_f32_e32 v30, v118, v158
	v_fmac_f32_e32 v34, v118, v162
	v_fmac_f32_e32 v31, v118, v166
	v_fmac_f32_e32 v30, v119, v159
	v_fmac_f32_e32 v34, v119, v163
	v_fmac_f32_e32 v31, v119, v167
	ds_read_b128 v[156:159], v35 offset:432
	ds_read_b128 v[160:163], v35 offset:4528
	ds_read_b128 v[164:167], v35 offset:8624
	s_waitcnt lgkmcnt(3)
	v_fmac_f32_e32 v30, v120, v144
	v_fmac_f32_e32 v34, v120, v148
	v_fmac_f32_e32 v31, v120, v152
	v_fmac_f32_e32 v30, v121, v145
	v_fmac_f32_e32 v34, v121, v149
	v_fmac_f32_e32 v31, v121, v153
	v_fmac_f32_e32 v30, v122, v146
	v_fmac_f32_e32 v34, v122, v150
	v_fmac_f32_e32 v31, v122, v154
	v_fmac_f32_e32 v30, v123, v147
	v_fmac_f32_e32 v34, v123, v151
	v_fmac_f32_e32 v31, v123, v155
	ds_read_b128 v[144:147], v35 offset:448
	ds_read_b128 v[148:151], v35 offset:4544
	ds_read_b128 v[152:155], v35 offset:8640
	s_waitcnt lgkmcnt(3)
	v_fmac_f32_e32 v30, v124, v156
	v_fmac_f32_e32 v34, v124, v160
	v_fmac_f32_e32 v31, v124, v164
	v_fmac_f32_e32 v30, v125, v157
	v_fmac_f32_e32 v34, v125, v161
	v_fmac_f32_e32 v31, v125, v165
	v_fmac_f32_e32 v30, v126, v158
	v_fmac_f32_e32 v34, v126, v162
	v_fmac_f32_e32 v31, v126, v166
	v_fmac_f32_e32 v30, v127, v159
	v_fmac_f32_e32 v34, v127, v163
	v_fmac_f32_e32 v31, v127, v167
	ds_read_b128 v[156:159], v35 offset:464
	ds_read_b128 v[160:163], v35 offset:4560
	ds_read_b128 v[164:167], v35 offset:8656
	s_waitcnt lgkmcnt(3)
	v_fmac_f32_e32 v30, v128, v144
	v_fmac_f32_e32 v34, v128, v148
	v_fmac_f32_e32 v31, v128, v152
	v_fmac_f32_e32 v30, v129, v145
	v_fmac_f32_e32 v34, v129, v149
	v_fmac_f32_e32 v31, v129, v153
	v_fmac_f32_e32 v30, v130, v146
	v_fmac_f32_e32 v34, v130, v150
	v_fmac_f32_e32 v31, v130, v154
	v_fmac_f32_e32 v30, v131, v147
	v_fmac_f32_e32 v34, v131, v151
	v_fmac_f32_e32 v31, v131, v155
	ds_read_b128 v[144:147], v35 offset:480
	ds_read_b128 v[148:151], v35 offset:4576
	ds_read_b128 v[152:155], v35 offset:8672
	s_waitcnt lgkmcnt(3)
	v_fmac_f32_e32 v30, v132, v156
	v_fmac_f32_e32 v34, v132, v160
	v_fmac_f32_e32 v31, v132, v164
	v_fmac_f32_e32 v30, v133, v157
	v_fmac_f32_e32 v34, v133, v161
	v_fmac_f32_e32 v31, v133, v165
	v_fmac_f32_e32 v30, v134, v158
	v_fmac_f32_e32 v34, v134, v162
	v_fmac_f32_e32 v31, v134, v166
	v_fmac_f32_e32 v30, v135, v159
	v_fmac_f32_e32 v34, v135, v163
	v_fmac_f32_e32 v31, v135, v167
	ds_read_b128 v[156:159], v35 offset:496
	ds_read_b128 v[160:163], v35 offset:4592
	ds_read_b128 v[164:167], v35 offset:8688
	s_waitcnt lgkmcnt(3)
	v_fmac_f32_e32 v30, v136, v144
	v_fmac_f32_e32 v34, v136, v148
	v_fmac_f32_e32 v31, v136, v152
	v_fmac_f32_e32 v30, v137, v145
	v_fmac_f32_e32 v34, v137, v149
	v_fmac_f32_e32 v31, v137, v153
	v_fmac_f32_e32 v30, v138, v146
	v_fmac_f32_e32 v34, v138, v150
	v_fmac_f32_e32 v31, v138, v154
	v_fmac_f32_e32 v30, v139, v147
	v_fmac_f32_e32 v34, v139, v151
	v_fmac_f32_e32 v31, v139, v155
	s_waitcnt lgkmcnt(0)
	v_fmac_f32_e32 v30, v140, v156
	v_fmac_f32_e32 v34, v140, v160
	v_fmac_f32_e32 v31, v140, v164
	v_fmac_f32_e32 v30, v141, v157
	v_fmac_f32_e32 v34, v141, v161
	v_fmac_f32_e32 v31, v141, v165
	v_fmac_f32_e32 v30, v142, v158
	v_fmac_f32_e32 v34, v142, v162
	v_fmac_f32_e32 v31, v142, v166
	v_fmac_f32_e32 v30, v143, v159
	v_fmac_f32_e32 v34, v143, v163
	v_fmac_f32_e32 v31, v143, v167
	ds_write2st64_b32 v19, v30, v34 offset0:52 offset1:53
	ds_write_b32 v19, v31 offset:13824
	s_waitcnt lgkmcnt(0)
	s_barrier
	s_and_saveexec_b64 s[4:5], vcc
	s_cbranch_execz .LBB0_27
	ds_read_b64 v[28:29], v23 offset:152
	s_mul_i32 s20, s39, 0x1800
	s_add_i32 s20, s20, s12
	v_or_b32_e32 v30, s20, v198
	v_ashrrev_i32_e32 v31, 31, v30
	s_waitcnt lgkmcnt(0)
	v_readfirstlane_b32 s21, v28
	v_readfirstlane_b32 s40, v29
	v_mov_b64_e32 v[40:41], s[10:11]
	v_mov_b32_e32 v28, s21
	v_mov_b32_e32 v29, s40
	v_lshl_add_u64 v[28:29], v[30:31], 2, v[28:29]
	global_load_dword v42, v[28:29], off
	ds_read2st64_b32 v[28:29], v33 offset0:52 offset1:55
	ds_read2st64_b32 v[30:31], v33 offset0:58 offset1:61
	ds_read2st64_b32 v[34:35], v33 offset0:64 offset1:67
	ds_read2st64_b32 v[36:37], v33 offset0:70 offset1:73
	v_mad_u64_u32 v[38:39], s[20:21], s39, 3, v[18:19]
	s_waitcnt lgkmcnt(3)
	v_add_f32_e32 v28, 0, v28
	v_add_f32_e32 v28, v28, v29
	s_waitcnt lgkmcnt(2)
	v_add_f32_e32 v28, v28, v30
	v_add_f32_e32 v28, v28, v31
	s_waitcnt lgkmcnt(1)
	v_add_f32_e32 v28, v28, v34
	v_add_f32_e32 v28, v28, v35
	v_mad_i64_i32 v[38:39], s[20:21], v38, s23, v[40:41]
	s_waitcnt lgkmcnt(0)
	v_add_f32_e32 v28, v28, v36
	v_lshl_add_u64 v[38:39], s[12:13], 2, v[38:39]
	v_add_f32_e32 v28, v28, v37
	s_waitcnt vmcnt(0)
	v_add_f32_e32 v30, v28, v42
	v_lshl_add_u64 v[28:29], v[38:39], 0, v[22:23]
	global_store_dword v[28:29], v30, off sc1
	s_branch .LBB0_27

.LBB0_85:
	v_add_u32_e32 v51, 0x400, v56
	ds_read2_b32 v[76:77], v51 offset1:65
	ds_read2_b32 v[78:79], v51 offset0:130 offset1:195
	v_add_u32_e32 v51, 0x800, v56
	s_ashr_i32 s18, s44, 31
	ds_read2_b32 v[80:81], v51 offset0:4 offset1:69
	ds_read2_b32 v[82:83], v51 offset0:134 offset1:199
	s_lshr_b32 s18, s18, 28
	s_add_i32 s18, s44, s18
	s_ashr_i32 s19, s18, 4
	s_waitcnt lgkmcnt(3)
	v_cvt_pk_bf16_f32 v76, v76, v77
	s_waitcnt lgkmcnt(2)
	v_cvt_pk_bf16_f32 v77, v78, v79
	s_waitcnt lgkmcnt(1)
	v_cvt_pk_bf16_f32 v78, v80, v81
	v_lshl_or_b32 v80, s19, 6, v55
	s_lshl_b32 s18, s19, 10
	v_ashrrev_i32_e32 v81, 31, v80
	s_sub_i32 s18, s13, s18
	v_lshlrev_b64 v[80:81], 11, v[80:81]
	v_lshl_add_u64 v[80:81], s[2:3], 0, v[80:81]
	s_ashr_i32 s19, s18, 31
	v_lshl_add_u64 v[80:81], s[18:19], 1, v[80:81]
	s_add_i32 s18, s56, s44
	s_waitcnt lgkmcnt(0)
	v_cvt_pk_bf16_f32 v79, v82, v83
	v_lshl_add_u64 v[80:81], v[80:81], 0, v[52:53]
	s_cmpk_gt_i32 s18, 0x1ff
	global_store_dwordx4 v[80:81], v[76:79], off sc1
	s_cbranch_scc0 .LBB0_88
	s_add_i32 s18, s36, s44
	s_cmpk_gt_i32 s18, 0x1ff
	s_cbranch_scc0 .LBB0_89

.LBB0_88:
	v_add_u32_e32 v51, 0x4400, v56
	ds_read2_b32 v[76:77], v51 offset0:64 offset1:129
	v_add_u32_e32 v51, 0x4600, v56
	ds_read2_b32 v[78:79], v51 offset0:66 offset1:131
	v_add_u32_e32 v51, 0x4800, v56
	s_ashr_i32 s19, s18, 31
	ds_read2_b32 v[80:81], v51 offset0:68 offset1:133
	s_lshr_b32 s19, s19, 28
	s_add_i32 s19, s18, s19
	s_and_b32 s20, s19, 0x3fffff0
	s_lshl_b32 s19, s19, 2
	v_add_u32_e32 v51, 0x4a00, v56
	s_andn2_b32 s19, s19, 63
	ds_read2_b32 v[82:83], v51 offset0:70 offset1:135
	s_waitcnt lgkmcnt(3)
	v_cvt_pk_bf16_f32 v76, v76, v77
	s_waitcnt lgkmcnt(2)
	v_cvt_pk_bf16_f32 v77, v78, v79
	s_waitcnt lgkmcnt(1)
	v_cvt_pk_bf16_f32 v78, v80, v81
	v_or_b32_e32 v80, s19, v55
	s_sub_i32 s18, s18, s20
	v_ashrrev_i32_e32 v81, 31, v80
	s_lshl_b32 s18, s18, 6
	v_lshlrev_b64 v[80:81], 11, v[80:81]
	v_lshl_add_u64 v[80:81], s[2:3], 0, v[80:81]
	s_ashr_i32 s19, s18, 31
	v_lshl_add_u64 v[80:81], s[18:19], 1, v[80:81]
	s_waitcnt lgkmcnt(0)
	v_cvt_pk_bf16_f32 v79, v82, v83
	v_lshl_add_u64 v[80:81], v[80:81], 0, v[52:53]
	global_store_dwordx4 v[80:81], v[76:79], off sc1
	s_add_i32 s18, s36, s44
	s_cmpk_gt_i32 s18, 0x1ff
	s_cbranch_scc1 .LBB0_87
.LBB0_89:
	v_add_u32_e32 v51, 0x8400, v56
	ds_read2_b32 v[76:77], v51 offset0:128 offset1:193
	v_add_u32_e32 v51, 0x8800, v56
	s_ashr_i32 s19, s18, 31
	ds_read2_b32 v[78:79], v51 offset0:2 offset1:67
	ds_read2_b32 v[80:81], v51 offset0:132 offset1:197
	s_lshr_b32 s19, s19, 28
	s_add_i32 s19, s18, s19
	s_and_b32 s20, s19, 0x3fffff0
	s_lshl_b32 s19, s19, 2
	v_add_u32_e32 v51, 0x8c00, v56
	s_andn2_b32 s19, s19, 63
	ds_read2_b32 v[82:83], v51 offset0:6 offset1:71
	s_waitcnt lgkmcnt(3)
	v_cvt_pk_bf16_f32 v76, v76, v77
	s_waitcnt lgkmcnt(2)
	v_cvt_pk_bf16_f32 v77, v78, v79
	s_waitcnt lgkmcnt(1)
	v_cvt_pk_bf16_f32 v78, v80, v81
	v_or_b32_e32 v80, s19, v55
	s_sub_i32 s18, s18, s20
	v_ashrrev_i32_e32 v81, 31, v80
	s_lshl_b32 s18, s18, 6
	v_lshlrev_b64 v[80:81], 11, v[80:81]
	v_lshl_add_u64 v[80:81], s[2:3], 0, v[80:81]
	s_ashr_i32 s19, s18, 31
	v_lshl_add_u64 v[80:81], s[18:19], 1, v[80:81]
	s_waitcnt lgkmcnt(0)
	v_cvt_pk_bf16_f32 v79, v82, v83
	v_lshl_add_u64 v[80:81], v[80:81], 0, v[52:53]
	global_store_dwordx4 v[80:81], v[76:79], off sc1
	s_add_i32 s18, s37, s44
	s_cmpk_gt_i32 s18, 0x1ff
	s_cbranch_scc1 .LBB0_52
.LBB0_90:
	v_add_u32_e32 v51, 0xc600, v56
	ds_read2_b32 v[76:77], v51 offset0:64 offset1:129
	v_add_u32_e32 v51, 0xc800, v56
	ds_read2_b32 v[78:79], v51 offset0:66 offset1:131
	v_add_u32_e32 v51, 0xca00, v56
	s_ashr_i32 s19, s18, 31
	ds_read2_b32 v[80:81], v51 offset0:68 offset1:133
	s_lshr_b32 s19, s19, 28
	s_add_i32 s19, s18, s19
	s_and_b32 s20, s19, 0x3fffff0
	s_lshl_b32 s19, s19, 2
	v_add_u32_e32 v51, 0xcc00, v56
	s_andn2_b32 s19, s19, 63
	ds_read2_b32 v[82:83], v51 offset0:70 offset1:135
	s_waitcnt lgkmcnt(3)
	v_cvt_pk_bf16_f32 v76, v76, v77
	s_waitcnt lgkmcnt(2)
	v_cvt_pk_bf16_f32 v77, v78, v79
	s_waitcnt lgkmcnt(1)
	v_cvt_pk_bf16_f32 v78, v80, v81
	v_or_b32_e32 v80, s19, v55
	s_sub_i32 s18, s18, s20
	v_ashrrev_i32_e32 v81, 31, v80
	s_lshl_b32 s18, s18, 6
	v_lshlrev_b64 v[80:81], 11, v[80:81]
	v_lshl_add_u64 v[80:81], s[2:3], 0, v[80:81]
	s_ashr_i32 s19, s18, 31
	v_lshl_add_u64 v[80:81], s[18:19], 1, v[80:81]
	s_waitcnt lgkmcnt(0)
	v_cvt_pk_bf16_f32 v79, v82, v83
	v_lshl_add_u64 v[80:81], v[80:81], 0, v[52:53]
	global_store_dwordx4 v[80:81], v[76:79], off sc1
	s_branch .LBB0_52

.LBB0_158:
	v_add_u32_e32 v51, 0x400, v56
	ds_read2_b32 v[76:77], v51 offset1:65
	ds_read2_b32 v[78:79], v51 offset0:130 offset1:195
	v_add_u32_e32 v51, 0x800, v56
	s_ashr_i32 s18, s13, 31
	ds_read2_b32 v[80:81], v51 offset0:4 offset1:69
	ds_read2_b32 v[82:83], v51 offset0:134 offset1:199
	s_lshr_b32 s18, s18, 30
	s_add_i32 s18, s13, s18
	s_ashr_i32 s19, s18, 2
	s_waitcnt lgkmcnt(3)
	v_cvt_pk_bf16_f32 v76, v76, v77
	s_waitcnt lgkmcnt(2)
	v_cvt_pk_bf16_f32 v77, v78, v79
	s_waitcnt lgkmcnt(1)
	v_cvt_pk_bf16_f32 v78, v80, v81
	v_lshl_or_b32 v80, s19, 6, v55
	s_lshl_b32 s18, s19, 8
	v_ashrrev_i32_e32 v81, 31, v80
	s_sub_i32 s18, s35, s18
	v_lshlrev_b64 v[80:81], 9, v[80:81]
	v_lshl_add_u64 v[80:81], s[2:3], 0, v[80:81]
	s_ashr_i32 s19, s18, 31
	v_lshl_add_u64 v[80:81], s[18:19], 1, v[80:81]
	s_add_i32 s18, s56, s13
	s_waitcnt lgkmcnt(0)
	v_cvt_pk_bf16_f32 v79, v82, v83
	v_lshl_add_u64 v[80:81], v[80:81], 0, v[52:53]
	s_cmp_gt_i32 s18, 47
	global_store_dwordx4 v[80:81], v[76:79], off sc1
	s_cbranch_scc0 .LBB0_161
	s_add_i32 s18, s37, s13
	s_cmp_gt_i32 s18, 47
	s_cbranch_scc0 .LBB0_162

.LBB0_161:
	v_add_u32_e32 v51, 0x4400, v56
	ds_read2_b32 v[76:77], v51 offset0:64 offset1:129
	v_add_u32_e32 v51, 0x4600, v56
	ds_read2_b32 v[78:79], v51 offset0:66 offset1:131
	v_add_u32_e32 v51, 0x4800, v56
	s_ashr_i32 s19, s18, 31
	ds_read2_b32 v[80:81], v51 offset0:68 offset1:133
	s_lshr_b32 s19, s19, 30
	s_add_i32 s19, s18, s19
	s_and_b32 s20, s19, 0x3fffffc
	s_lshl_b32 s19, s19, 4
	v_add_u32_e32 v51, 0x4a00, v56
	s_andn2_b32 s19, s19, 63
	ds_read2_b32 v[82:83], v51 offset0:70 offset1:135
	s_waitcnt lgkmcnt(3)
	v_cvt_pk_bf16_f32 v76, v76, v77
	s_waitcnt lgkmcnt(2)
	v_cvt_pk_bf16_f32 v77, v78, v79
	s_waitcnt lgkmcnt(1)
	v_cvt_pk_bf16_f32 v78, v80, v81
	v_or_b32_e32 v80, s19, v55
	s_sub_i32 s18, s18, s20
	v_ashrrev_i32_e32 v81, 31, v80
	s_lshl_b32 s18, s18, 6
	v_lshlrev_b64 v[80:81], 9, v[80:81]
	v_lshl_add_u64 v[80:81], s[2:3], 0, v[80:81]
	s_ashr_i32 s19, s18, 31
	v_lshl_add_u64 v[80:81], s[18:19], 1, v[80:81]
	s_waitcnt lgkmcnt(0)
	v_cvt_pk_bf16_f32 v79, v82, v83
	v_lshl_add_u64 v[80:81], v[80:81], 0, v[52:53]
	global_store_dwordx4 v[80:81], v[76:79], off sc1
	s_add_i32 s18, s37, s13
	s_cmp_gt_i32 s18, 47
	s_cbranch_scc1 .LBB0_160
.LBB0_162:
	v_add_u32_e32 v51, 0x8400, v56
	ds_read2_b32 v[76:77], v51 offset0:128 offset1:193
	v_add_u32_e32 v51, 0x8800, v56
	s_ashr_i32 s19, s18, 31
	ds_read2_b32 v[78:79], v51 offset0:2 offset1:67
	ds_read2_b32 v[80:81], v51 offset0:132 offset1:197
	s_lshr_b32 s19, s19, 30
	s_add_i32 s19, s18, s19
	s_and_b32 s20, s19, 0x3fffffc
	s_lshl_b32 s19, s19, 4
	v_add_u32_e32 v51, 0x8c00, v56
	s_andn2_b32 s19, s19, 63
	ds_read2_b32 v[82:83], v51 offset0:6 offset1:71
	s_waitcnt lgkmcnt(3)
	v_cvt_pk_bf16_f32 v76, v76, v77
	s_waitcnt lgkmcnt(2)
	v_cvt_pk_bf16_f32 v77, v78, v79
	s_waitcnt lgkmcnt(1)
	v_cvt_pk_bf16_f32 v78, v80, v81
	v_or_b32_e32 v80, s19, v55
	s_sub_i32 s18, s18, s20
	v_ashrrev_i32_e32 v81, 31, v80
	s_lshl_b32 s18, s18, 6
	v_lshlrev_b64 v[80:81], 9, v[80:81]
	v_lshl_add_u64 v[80:81], s[2:3], 0, v[80:81]
	s_ashr_i32 s19, s18, 31
	v_lshl_add_u64 v[80:81], s[18:19], 1, v[80:81]
	s_waitcnt lgkmcnt(0)
	v_cvt_pk_bf16_f32 v79, v82, v83
	v_lshl_add_u64 v[80:81], v[80:81], 0, v[52:53]
	global_store_dwordx4 v[80:81], v[76:79], off sc1
	s_add_i32 s13, s38, s13
	s_cmp_gt_i32 s13, 47
	s_cbranch_scc1 .LBB0_125
.LBB0_163:
	v_add_u32_e32 v51, 0xc600, v56
	s_ashr_i32 s18, s13, 31
	ds_read2_b32 v[76:77], v51 offset0:64 offset1:129
	v_add_u32_e32 v51, 0xc800, v56
	s_lshr_b32 s18, s18, 30
	ds_read2_b32 v[78:79], v51 offset0:66 offset1:131
	v_add_u32_e32 v51, 0xca00, v56
	s_add_i32 s19, s13, s18
	ds_read2_b32 v[80:81], v51 offset0:68 offset1:133
	s_and_b32 s18, s19, 0x3fffffc
	s_sub_i32 s13, s13, s18
	s_lshl_b32 s18, s13, 6
	s_lshl_b32 s13, s19, 4
	v_add_u32_e32 v51, 0xcc00, v56
	s_andn2_b32 s13, s13, 63
	ds_read2_b32 v[82:83], v51 offset0:70 offset1:135
	s_waitcnt lgkmcnt(3)
	v_cvt_pk_bf16_f32 v76, v76, v77
	s_waitcnt lgkmcnt(2)
	v_cvt_pk_bf16_f32 v77, v78, v79
	s_waitcnt lgkmcnt(1)
	v_cvt_pk_bf16_f32 v78, v80, v81
	v_or_b32_e32 v80, s13, v55
	v_ashrrev_i32_e32 v81, 31, v80
	v_lshlrev_b64 v[80:81], 9, v[80:81]
	v_lshl_add_u64 v[80:81], s[2:3], 0, v[80:81]
	s_ashr_i32 s19, s18, 31
	v_lshl_add_u64 v[80:81], s[18:19], 1, v[80:81]
	s_waitcnt lgkmcnt(0)
	v_cvt_pk_bf16_f32 v79, v82, v83
	v_lshl_add_u64 v[80:81], v[80:81], 0, v[52:53]
	global_store_dwordx4 v[80:81], v[76:79], off sc1
	s_branch .LBB0_125

.LBB0_231:
	v_add_u32_e32 v51, 0x400, v56
	ds_read2_b32 v[76:77], v51 offset1:65
	ds_read2_b32 v[78:79], v51 offset0:130 offset1:195
	v_add_u32_e32 v51, 0x800, v56
	ds_read2_b32 v[80:81], v51 offset0:4 offset1:69
	ds_read2_b32 v[82:83], v51 offset0:134 offset1:199
	s_lshr_b32 s18, s13, 31
	s_add_i32 s18, s13, s18
	s_ashr_i32 s19, s18, 1
	s_waitcnt lgkmcnt(3)
	v_cvt_pk_bf16_f32 v76, v76, v77
	s_waitcnt lgkmcnt(2)
	v_cvt_pk_bf16_f32 v77, v78, v79
	s_waitcnt lgkmcnt(1)
	v_cvt_pk_bf16_f32 v78, v80, v81
	v_lshl_or_b32 v80, s19, 6, v55
	s_lshl_b32 s18, s19, 7
	v_ashrrev_i32_e32 v81, 31, v80
	s_sub_i32 s18, s27, s18
	v_lshlrev_b64 v[80:81], 8, v[80:81]
	v_lshl_add_u64 v[80:81], s[2:3], 0, v[80:81]
	s_ashr_i32 s19, s18, 31
	v_lshl_add_u64 v[80:81], s[18:19], 1, v[80:81]
	s_add_i32 s18, s56, s13
	s_waitcnt lgkmcnt(0)
	v_cvt_pk_bf16_f32 v79, v82, v83
	v_lshl_add_u64 v[80:81], v[80:81], 0, v[52:53]
	s_cmp_gt_i32 s18, 31
	global_store_dwordx4 v[80:81], v[76:79], off sc1
	s_cbranch_scc0 .LBB0_234
	s_add_i32 s18, s29, s13
	s_cmp_gt_i32 s18, 31
	s_cbranch_scc0 .LBB0_235

.LBB0_234:
	v_add_u32_e32 v51, 0x4400, v56
	ds_read2_b32 v[76:77], v51 offset0:64 offset1:129
	v_add_u32_e32 v51, 0x4600, v56
	ds_read2_b32 v[78:79], v51 offset0:66 offset1:131
	v_add_u32_e32 v51, 0x4800, v56
	ds_read2_b32 v[80:81], v51 offset0:68 offset1:133
	s_lshr_b32 s19, s18, 31
	s_add_i32 s19, s18, s19
	s_and_b32 s20, s19, 0x3fffffe
	s_lshl_b32 s19, s19, 5
	v_add_u32_e32 v51, 0x4a00, v56
	s_andn2_b32 s19, s19, 63
	ds_read2_b32 v[82:83], v51 offset0:70 offset1:135
	s_waitcnt lgkmcnt(3)
	v_cvt_pk_bf16_f32 v76, v76, v77
	s_waitcnt lgkmcnt(2)
	v_cvt_pk_bf16_f32 v77, v78, v79
	s_waitcnt lgkmcnt(1)
	v_cvt_pk_bf16_f32 v78, v80, v81
	v_or_b32_e32 v80, s19, v55
	s_sub_i32 s18, s18, s20
	v_ashrrev_i32_e32 v81, 31, v80
	s_lshl_b32 s18, s18, 6
	v_lshlrev_b64 v[80:81], 8, v[80:81]
	v_lshl_add_u64 v[80:81], s[2:3], 0, v[80:81]
	s_ashr_i32 s19, s18, 31
	v_lshl_add_u64 v[80:81], s[18:19], 1, v[80:81]
	s_waitcnt lgkmcnt(0)
	v_cvt_pk_bf16_f32 v79, v82, v83
	v_lshl_add_u64 v[80:81], v[80:81], 0, v[52:53]
	global_store_dwordx4 v[80:81], v[76:79], off sc1
	s_add_i32 s18, s29, s13
	s_cmp_gt_i32 s18, 31
	s_cbranch_scc1 .LBB0_233
.LBB0_235:
	v_add_u32_e32 v51, 0x8400, v56
	ds_read2_b32 v[76:77], v51 offset0:128 offset1:193
	v_add_u32_e32 v51, 0x8800, v56
	ds_read2_b32 v[78:79], v51 offset0:2 offset1:67
	ds_read2_b32 v[80:81], v51 offset0:132 offset1:197
	s_lshr_b32 s19, s18, 31
	s_add_i32 s19, s18, s19
	s_and_b32 s20, s19, 0x3fffffe
	s_lshl_b32 s19, s19, 5
	v_add_u32_e32 v51, 0x8c00, v56
	s_andn2_b32 s19, s19, 63
	ds_read2_b32 v[82:83], v51 offset0:6 offset1:71
	s_waitcnt lgkmcnt(3)
	v_cvt_pk_bf16_f32 v76, v76, v77
	s_waitcnt lgkmcnt(2)
	v_cvt_pk_bf16_f32 v77, v78, v79
	s_waitcnt lgkmcnt(1)
	v_cvt_pk_bf16_f32 v78, v80, v81
	v_or_b32_e32 v80, s19, v55
	s_sub_i32 s18, s18, s20
	v_ashrrev_i32_e32 v81, 31, v80
	s_lshl_b32 s18, s18, 6
	v_lshlrev_b64 v[80:81], 8, v[80:81]
	v_lshl_add_u64 v[80:81], s[2:3], 0, v[80:81]
	s_ashr_i32 s19, s18, 31
	v_lshl_add_u64 v[80:81], s[18:19], 1, v[80:81]
	s_waitcnt lgkmcnt(0)
	v_cvt_pk_bf16_f32 v79, v82, v83
	v_lshl_add_u64 v[80:81], v[80:81], 0, v[52:53]
	global_store_dwordx4 v[80:81], v[76:79], off sc1
	s_add_i32 s13, s34, s13
	s_cmp_gt_i32 s13, 31
	s_cbranch_scc1 .LBB0_198
.LBB0_236:
	v_add_u32_e32 v51, 0xc600, v56
	ds_read2_b32 v[76:77], v51 offset0:64 offset1:129
	v_add_u32_e32 v51, 0xc800, v56
	s_lshr_b32 s18, s13, 31
	ds_read2_b32 v[78:79], v51 offset0:66 offset1:131
	v_add_u32_e32 v51, 0xca00, v56
	s_add_i32 s19, s13, s18
	ds_read2_b32 v[80:81], v51 offset0:68 offset1:133
	s_and_b32 s18, s19, 0x3fffffe
	s_sub_i32 s13, s13, s18
	s_lshl_b32 s18, s13, 6
	s_lshl_b32 s13, s19, 5
	v_add_u32_e32 v51, 0xcc00, v56
	s_andn2_b32 s13, s13, 63
	ds_read2_b32 v[82:83], v51 offset0:70 offset1:135
	s_waitcnt lgkmcnt(3)
	v_cvt_pk_bf16_f32 v76, v76, v77
	s_waitcnt lgkmcnt(2)
	v_cvt_pk_bf16_f32 v77, v78, v79
	s_waitcnt lgkmcnt(1)
	v_cvt_pk_bf16_f32 v78, v80, v81
	v_or_b32_e32 v80, s13, v55
	v_ashrrev_i32_e32 v81, 31, v80
	v_lshlrev_b64 v[80:81], 8, v[80:81]
	v_lshl_add_u64 v[80:81], s[2:3], 0, v[80:81]
	s_ashr_i32 s19, s18, 31
	v_lshl_add_u64 v[80:81], s[18:19], 1, v[80:81]
	s_waitcnt lgkmcnt(0)
	v_cvt_pk_bf16_f32 v79, v82, v83
	v_lshl_add_u64 v[80:81], v[80:81], 0, v[52:53]
	global_store_dwordx4 v[80:81], v[76:79], off sc1
	s_branch .LBB0_198

.LBB0_238:
	s_andn2_b64 vcc, exec, s[20:21]
	s_cbranch_vccnz .LBB0_276
	s_waitcnt vmcnt(0)
	v_add_u32_e32 v18, 0x400, v57
	ds_write2_b32 v18, v2, v3 offset1:1
	v_add_u32_e32 v2, 0x408, v57
	ds_write2_b32 v2, v4, v5 offset1:1
	v_add_u32_e32 v2, 0x2480, v57
	ds_write2_b32 v2, v6, v7 offset1:1
	v_add_u32_e32 v2, 0x2488, v57
	ds_write2_b32 v2, v8, v9 offset1:1
	v_add_u32_e32 v2, 0x4500, v57
	s_add_u32 s2, s25, 0x28000
	ds_write2_b32 v2, v10, v11 offset1:1
	v_add_u32_e32 v2, 0x4508, v57
	s_addc_u32 s3, s26, 0
	ds_write2_b32 v2, v12, v13 offset1:1
	v_add_u32_e32 v2, 0x6580, v57
	s_cmpk_gt_i32 s7, 0x1ff
	ds_write2_b32 v2, v14, v15 offset1:1
	v_add_u32_e32 v2, 0x6588, v57
	v_lshlrev_b32_e32 v18, 1, v58
	ds_write2_b32 v2, v16, v17 offset1:1
	s_waitcnt lgkmcnt(0)
	s_barrier
	s_cbranch_scc1 .LBB0_241
	v_add_u32_e32 v2, s8, v55
	v_ashrrev_i32_e32 v3, 31, v2
	v_add_u32_e32 v4, 0x400, v56
	v_add_u32_e32 v10, 0x800, v56
	v_lshlrev_b64 v[6:7], 11, v[2:3]
	ds_read2_b32 v[2:3], v4 offset1:65
	ds_read2_b32 v[4:5], v4 offset0:130 offset1:195
	ds_read2_b32 v[8:9], v10 offset0:4 offset1:69
	ds_read2_b32 v[10:11], v10 offset0:134 offset1:199
	s_ashr_i32 s7, s6, 31
	v_lshl_add_u64 v[6:7], s[2:3], 0, v[6:7]
	v_lshl_add_u64 v[6:7], s[6:7], 1, v[6:7]
	v_mov_b32_e32 v19, 0
	s_waitcnt lgkmcnt(3)
	v_cvt_pk_bf16_f32 v2, v2, v3
	s_waitcnt lgkmcnt(2)
	v_cvt_pk_bf16_f32 v3, v4, v5
	s_waitcnt lgkmcnt(1)
	v_cvt_pk_bf16_f32 v4, v8, v9
	s_waitcnt lgkmcnt(0)
	v_cvt_pk_bf16_f32 v5, v10, v11
	v_lshl_add_u64 v[6:7], v[6:7], 0, v[18:19]
	global_store_dwordx4 v[6:7], v[2:5], off sc1
.LBB0_241:
	s_cmpk_gt_i32 s11, 0x1ff
	s_cbranch_scc1 .LBB0_243
	v_add_u32_e32 v2, s12, v55
	v_ashrrev_i32_e32 v3, 31, v2
	v_lshlrev_b64 v[6:7], 11, v[2:3]
	v_add_u32_e32 v2, 0x4400, v56
	v_add_u32_e32 v4, 0x4600, v56
	v_add_u32_e32 v8, 0x4800, v56
	v_add_u32_e32 v10, 0x4a00, v56
	ds_read2_b32 v[2:3], v2 offset0:64 offset1:129
	ds_read2_b32 v[4:5], v4 offset0:66 offset1:131
	ds_read2_b32 v[8:9], v8 offset0:68 offset1:133
	ds_read2_b32 v[10:11], v10 offset0:70 offset1:135
	s_ashr_i32 s11, s10, 31
	v_lshl_add_u64 v[6:7], s[2:3], 0, v[6:7]
	v_lshl_add_u64 v[6:7], s[10:11], 1, v[6:7]
	v_mov_b32_e32 v19, 0
	s_waitcnt lgkmcnt(3)
	v_cvt_pk_bf16_f32 v2, v2, v3
	s_waitcnt lgkmcnt(2)
	v_cvt_pk_bf16_f32 v3, v4, v5
	s_waitcnt lgkmcnt(1)
	v_cvt_pk_bf16_f32 v4, v8, v9
	s_waitcnt lgkmcnt(0)
	v_cvt_pk_bf16_f32 v5, v10, v11
	v_lshl_add_u64 v[6:7], v[6:7], 0, v[18:19]
	global_store_dwordx4 v[6:7], v[2:5], off sc1

.LBB0_256:
	s_and_b64 vcc, exec, s[2:3]
	s_cbranch_vccnz .LBB0_260
	v_add_u32_e32 v19, 0x400, v57
	s_waitcnt vmcnt(0)
	ds_write2_b32 v19, v6, v7 offset1:1
	v_add_u32_e32 v6, 0x408, v57
	ds_write2_b32 v6, v8, v9 offset1:1
	v_add_u32_e32 v6, 0x2480, v57
	ds_write2_b32 v6, v2, v3 offset1:1
	v_add_u32_e32 v2, 0x2488, v57
	ds_write2_b32 v2, v4, v5 offset1:1
	v_add_u32_e32 v2, 0x4500, v57
	ds_write2_b32 v2, v14, v15 offset1:1
	v_add_u32_e32 v2, 0x4508, v57
	ds_write2_b32 v2, v16, v17 offset1:1
	v_add_u32_e32 v2, 0x6580, v57
	ds_write2_b32 v2, v10, v11 offset1:1
	v_add_u32_e32 v2, 0x6588, v57
	ds_write2_b32 v2, v12, v13 offset1:1
	v_add_u32_e32 v2, 0x8600, v57
	v_mov_b32_e32 v19, 0
	ds_write2_b32 v2, v19, v19 offset1:1
	v_add_u32_e32 v2, 0x8608, v57
	ds_write2_b32 v2, v19, v19 offset1:1
	v_add_u32_e32 v2, 0xa680, v57
	ds_write2_b32 v2, v19, v19 offset1:1
	v_add_u32_e32 v2, 0xa688, v57
	ds_write2_b32 v2, v19, v19 offset1:1
	v_add_u32_e32 v2, 0xc700, v57
	ds_write2_b32 v2, v19, v19 offset1:1
	v_add_u32_e32 v2, 0xc708, v57
	ds_write2_b32 v2, v19, v19 offset1:1
	v_add_u32_e32 v2, 0xe780, v57
	s_add_u32 s2, s10, 0x428000
	ds_write2_b32 v2, v19, v19 offset1:1
	v_add_u32_e32 v2, 0xe788, v57
	v_add_u32_e32 v4, 0x400, v56
	s_addc_u32 s3, s11, 0
	ds_write2_b32 v2, v19, v19 offset1:1
	s_waitcnt lgkmcnt(0)
	s_barrier
	s_bfe_u32 s4, s12, 0x2001d
	ds_read2_b32 v[2:3], v4 offset1:65
	ds_read2_b32 v[4:5], v4 offset0:130 offset1:195
	v_add_u32_e32 v8, 0x800, v56
	s_add_i32 s4, s12, s4
	ds_read2_b32 v[6:7], v8 offset0:4 offset1:69
	ds_read2_b32 v[8:9], v8 offset0:134 offset1:199
	s_and_b32 s6, s4, 0xfffc
	s_sext_i32_i16 s4, s4
	s_lshl_b32 s4, s4, 4
	s_andn2_b32 s4, s4, 63
	s_sub_i32 s6, s12, s6
	s_waitcnt lgkmcnt(3)
	v_cvt_pk_bf16_f32 v2, v2, v3
	s_waitcnt lgkmcnt(2)
	v_cvt_pk_bf16_f32 v3, v4, v5
	s_waitcnt lgkmcnt(1)
	v_cvt_pk_bf16_f32 v4, v6, v7
	v_or_b32_e32 v6, s4, v55
	s_sext_i32_i16 s6, s6
	v_ashrrev_i32_e32 v7, 31, v6
	s_lshl_b32 s6, s6, 6
	v_lshlrev_b64 v[6:7], 9, v[6:7]
	v_lshl_add_u64 v[6:7], s[2:3], 0, v[6:7]
	s_ashr_i32 s7, s6, 31
	v_lshl_add_u64 v[6:7], s[6:7], 1, v[6:7]
	s_mov_b32 s5, 0
	s_waitcnt lgkmcnt(0)
	v_cvt_pk_bf16_f32 v5, v8, v9
	v_lshl_add_u64 v[6:7], v[6:7], 0, v[18:19]
	s_cmpk_gt_i32 s12, 0xff2f
	global_store_dwordx4 v[6:7], v[2:5], off sc1
	s_cbranch_scc1 .LBB0_259
	s_nop 0
	v_add_u32_e32 v2, 0x4400, v56
	v_add_u32_e32 v4, 0x4600, v56
	v_add_u32_e32 v6, 0x4800, v56
	ds_read2_b32 v[2:3], v2 offset0:64 offset1:129
	ds_read2_b32 v[4:5], v4 offset0:66 offset1:131
	ds_read2_b32 v[6:7], v6 offset0:68 offset1:133
	s_lshl_b32 s4, s12, 4
	s_andn2_b32 s4, s4, 63
	v_add_u32_e32 v8, 0x4a00, v56
	s_addk_i32 s4, 0x1000
	ds_read2_b32 v[8:9], v8 offset0:70 offset1:135
	s_waitcnt lgkmcnt(3)
	v_cvt_pk_bf16_f32 v2, v2, v3
	s_waitcnt lgkmcnt(2)
	v_cvt_pk_bf16_f32 v3, v4, v5
	s_waitcnt lgkmcnt(1)
	v_cvt_pk_bf16_f32 v4, v6, v7
	v_or_b32_e32 v6, s4, v55
	v_mov_b32_e32 v7, v19
	v_lshlrev_b64 v[6:7], 9, v[6:7]
	v_lshl_add_u64 v[6:7], s[2:3], 0, v[6:7]
	s_lshl_b32 s2, s12, 7
	s_and_b32 s4, s2, 0x180
	v_lshl_add_u64 v[6:7], v[6:7], 0, s[4:5]
	s_waitcnt lgkmcnt(0)
	v_cvt_pk_bf16_f32 v5, v8, v9
	v_lshl_add_u64 v[6:7], v[6:7], 0, v[18:19]
	global_store_dwordx4 v[6:7], v[2:5], off sc1

.LBB0_272:
	s_and_b64 vcc, exec, s[2:3]
	s_cbranch_vccnz .LBB0_276
	v_add_u32_e32 v1, 0x400, v57
	s_waitcnt vmcnt(0)
	ds_write2_b32 v1, v6, v7 offset1:1
	v_add_u32_e32 v1, 0x408, v57
	ds_write2_b32 v1, v8, v9 offset1:1
	v_add_u32_e32 v1, 0x2480, v57
	ds_write2_b32 v1, v2, v3 offset1:1
	v_add_u32_e32 v1, 0x2488, v57
	ds_write2_b32 v1, v4, v5 offset1:1
	v_add_u32_e32 v1, 0x4500, v57
	ds_write2_b32 v1, v14, v15 offset1:1
	v_add_u32_e32 v1, 0x4508, v57
	ds_write2_b32 v1, v16, v17 offset1:1
	v_add_u32_e32 v1, 0x6580, v57
	ds_write2_b32 v1, v10, v11 offset1:1
	v_add_u32_e32 v1, 0x6588, v57
	ds_write2_b32 v1, v12, v13 offset1:1
	v_add_u32_e32 v1, 0x8600, v57
	v_mov_b32_e32 v19, 0
	ds_write2_b32 v1, v19, v19 offset1:1
	v_add_u32_e32 v1, 0x8608, v57
	ds_write2_b32 v1, v19, v19 offset1:1
	v_add_u32_e32 v1, 0xa680, v57
	ds_write2_b32 v1, v19, v19 offset1:1
	v_add_u32_e32 v1, 0xa688, v57
	ds_write2_b32 v1, v19, v19 offset1:1
	v_add_u32_e32 v1, 0xc700, v57
	ds_write2_b32 v1, v19, v19 offset1:1
	v_add_u32_e32 v1, 0xc708, v57
	ds_write2_b32 v1, v19, v19 offset1:1
	v_add_u32_e32 v1, 0xe780, v57
	ds_write2_b32 v1, v19, v19 offset1:1
	v_add_u32_e32 v1, 0xe788, v57
	s_add_u32 s2, s10, 0x488000
	ds_write2_b32 v1, v19, v19 offset1:1
	v_add_u32_e32 v1, 0x400, v56
	s_addc_u32 s3, s11, 0
	s_waitcnt lgkmcnt(0)
	s_barrier
	s_bfe_u32 s6, s12, 0x1000f
	ds_read2_b32 v[2:3], v1 offset1:65
	ds_read2_b32 v[4:5], v1 offset0:130 offset1:195
	v_add_u32_e32 v1, 0x800, v56
	s_add_i32 s6, s12, s6
	ds_read2_b32 v[6:7], v1 offset0:4 offset1:69
	ds_read2_b32 v[8:9], v1 offset0:134 offset1:199
	s_and_b32 s8, s6, 0xfffe
	s_sext_i32_i16 s6, s6
	s_lshl_b32 s6, s6, 5
	s_andn2_b32 s6, s6, 63
	s_sub_i32 s8, s12, s8
	s_waitcnt lgkmcnt(3)
	v_cvt_pk_bf16_f32 v2, v2, v3
	s_waitcnt lgkmcnt(2)
	v_cvt_pk_bf16_f32 v3, v4, v5
	s_waitcnt lgkmcnt(1)
	v_cvt_pk_bf16_f32 v4, v6, v7
	v_or_b32_e32 v6, s6, v55
	s_sext_i32_i16 s8, s8
	v_ashrrev_i32_e32 v7, 31, v6
	s_lshl_b32 s8, s8, 6
	v_lshlrev_b64 v[6:7], 8, v[6:7]
	v_lshl_add_u64 v[6:7], s[2:3], 0, v[6:7]
	s_ashr_i32 s9, s8, 31
	v_lshl_add_u64 v[6:7], s[8:9], 1, v[6:7]
	s_mov_b32 s7, 0
	s_waitcnt lgkmcnt(0)
	v_cvt_pk_bf16_f32 v5, v8, v9
	v_lshl_add_u64 v[6:7], v[6:7], 0, v[18:19]
	s_and_b64 vcc, exec, s[4:5]
	global_store_dwordx4 v[6:7], v[2:5], off sc1
	s_cbranch_vccnz .LBB0_275
	v_add_u32_e32 v1, 0x4400, v56
	ds_read2_b32 v[2:3], v1 offset0:64 offset1:129
	v_add_u32_e32 v1, 0x4600, v56
	ds_read2_b32 v[4:5], v1 offset0:66 offset1:131
	v_add_u32_e32 v1, 0x4800, v56
	ds_read2_b32 v[6:7], v1 offset0:68 offset1:133
	s_lshl_b32 s4, s12, 5
	s_andn2_b32 s4, s4, 63
	v_add_u32_e32 v1, 0x4a00, v56
	s_addk_i32 s4, 0x2000
	ds_read2_b32 v[8:9], v1 offset0:70 offset1:135
	s_waitcnt lgkmcnt(3)
	v_cvt_pk_bf16_f32 v2, v2, v3
	s_waitcnt lgkmcnt(2)
	v_cvt_pk_bf16_f32 v3, v4, v5
	s_waitcnt lgkmcnt(1)
	v_cvt_pk_bf16_f32 v4, v6, v7
	v_or_b32_e32 v6, s4, v55
	v_mov_b32_e32 v7, v19
	v_lshlrev_b64 v[6:7], 8, v[6:7]
	v_lshl_add_u64 v[6:7], s[2:3], 0, v[6:7]
	s_lshl_b32 s2, s12, 7
	s_and_b32 s6, s2, 0x80
	v_lshl_add_u64 v[6:7], v[6:7], 0, s[6:7]
	s_waitcnt lgkmcnt(0)
	v_cvt_pk_bf16_f32 v5, v8, v9
	v_lshl_add_u64 v[6:7], v[6:7], 0, v[18:19]
	global_store_dwordx4 v[6:7], v[2:5], off sc1

.LBB0_276:
	s_cmp_lt_i32 s59, 2
	s_barrier
	s_cbranch_scc1 .LBB0_330
	s_waitcnt vmcnt(0)
	s_barrier
	s_and_saveexec_b64 s[2:3], s[0:1]
	s_cbranch_execz .LBB0_329
	s_waitcnt vmcnt(0) lgkmcnt(0)
	v_mov_b32_e32 v241, 0
	v_lshlrev_b32_e64 v254, 8, s31
	v_mov_b32_e32 v247, 1
	v_mov_b32_e32 v246, 0x3600
	global_atomic_add v248, v246, v247, s[60:61] sc0
